# branch-merge GEMM loop: priority toggling around the MFMA blocks removed as well
# speedup vs baseline: 1.0130x; 1.0000x over previous
.Lp6_top:
	s_mul_hi_u32 s4, s23, 0xaaaaaaab
	s_lshr_b32 s5, s4, 1
	s_mul_i32 s5, s5, 0x24000
	v_add_u32_e32 v140, s20, v156
	v_subrev_u32_e32 v141, s5, v157
	v_subrev_u32_e32 v142, s5, v160
	v_add_u32_e32 v142, v140, v142
	v_add_u32_e32 v144, v140, v141
	ds_read_b128 v[194:197], v142
	ds_read_b128 v[198:201], v142 offset:2048
	ds_read_b128 v[202:205], v142 offset:4096
	ds_read_b128 v[206:209], v142 offset:6144
	ds_read_b128 v[210:213], v144 offset:32768
	ds_read_b128 v[214:217], v144 offset:34816
	ds_read_b128 v[218:221], v144 offset:36864
	ds_read_b128 v[222:225], v144 offset:38912
	s_add_i32 s12, s23, 2
	s_cmp_ge_u32 s12, s18
	s_cselect_b64 s[10:11], -1, 0

	s_waitcnt lgkmcnt(8)
	s_and_b64 vcc, exec, s[10:11]
	s_cbranch_vccnz .Lp6_m0_plain
	v_mfma_f32_16x16x32_bf16 v[60:63], v[178:181], v[162:165], v[60:63]
	s_mul_hi_u32 s0, s21, 0xaaaaaaab
	s_lshr_b32 s1, s0, 1
	s_lshr_b32 s0, s0, 4
	s_mul_i32 s0, s0, 24
	s_mul_i32 s1, s1, 0x24000
	v_mfma_f32_16x16x32_bf16 v[56:59], v[182:185], v[162:165], v[56:59]
	s_sub_i32 s0, s23, s0
	v_subrev_u32_e32 v141, s1, v146
	s_add_i32 s1, s20, 0
	s_add_i32 s0, s0, 2
	v_add_u32_e32 v141, s1, v141
	v_mfma_f32_16x16x32_bf16 v[52:55], v[186:189], v[162:165], v[52:55]
	s_mul_hi_u32 s1, s12, 0xaaaaaaab
	s_ashr_i32 s0, s0, 3
	s_lshr_b32 s24, s1, 4
	s_ashr_i32 s1, s0, 31
	s_lshl_b64 s[12:13], s[0:1], 20
	v_mfma_f32_16x16x32_bf16 v[48:51], v[190:193], v[162:165], v[48:51]
	s_add_u32 s12, s14, s12
	s_addc_u32 s13, s15, s13
	s_and_b32 s25, s22, 0x1c0
	s_lshl_b32 s25, s25, 1
	s_add_u32 s12, s12, s25
	v_mfma_f32_16x16x32_bf16 v[44:47], v[178:181], v[166:169], v[44:47]
	s_addc_u32 s13, s13, 0
	s_lshl_b64 s[0:1], s[0:1], 24
	s_add_u32 s0, s16, s0
	s_addc_u32 s1, s17, s1
	s_add_u32 s25, s0, s25
	v_mfma_f32_16x16x32_bf16 v[40:43], v[182:185], v[166:169], v[40:43]
	s_addc_u32 s27, s1, 0
	s_mov_b32 s26, s43
	s_lshr_b32 s0, s26, 16
	s_cmp_lg_u32 s0, 0
	s_cselect_b64 s[0:1], -1, 0
	v_mfma_f32_16x16x32_bf16 v[36:39], v[186:189], v[166:169], v[36:39]
	s_cmp_lg_u64 s[0:1], 0
	s_addc_u32 s0, s40, 0
	s_mul_i32 s0, s0, s24
	s_add_i32 s24, s0, s2
	s_lshr_b32 s1, s24, 3
	v_mfma_f32_16x16x32_bf16 v[32:35], v[190:193], v[166:169], v[32:35]
	s_and_b32 s0, s24, 7
	s_and_b32 s1, s1, 0xfffff8
	s_or_b32 s0, s1, s0
	s_lshl_b32 s0, s0, 8
	s_ashr_i32 s1, s0, 31
	v_mfma_f32_16x16x32_bf16 v[28:31], v[178:181], v[170:173], v[28:31]
	s_lshl_b64 s[0:1], s[0:1], 10
	v_add_u32_e32 v144, 0x18000, v141
	s_add_u32 s0, s25, s0
	v_add_u32_e32 v152, 0x22000, v141
	v_add_u32_e32 v153, 0x20000, v141
	v_mfma_f32_16x16x32_bf16 v[24:27], v[182:185], v[170:173], v[24:27]
	v_add_u32_e32 v161, 0x1e000, v141
	v_add_u32_e32 v140, 0x1c000, v141
	v_add_u32_e32 v141, 0x1a000, v141
	s_addc_u32 s1, s27, s1
	v_readfirstlane_b32 s25, v144
	v_mfma_f32_16x16x32_bf16 v[20:23], v[186:189], v[170:173], v[20:23]
	v_lshl_add_u64 v[142:143], v[64:65], 1, s[0:1]
	s_mov_b32 m0, s25
	v_readfirstlane_b32 s25, v141
	global_load_lds_dwordx4 v[142:143], off
	v_lshl_add_u64 v[142:143], v[66:67], 1, s[0:1]
	v_mfma_f32_16x16x32_bf16 v[16:19], v[190:193], v[170:173], v[16:19]
	s_mov_b32 m0, s25
	v_readfirstlane_b32 s25, v140
	s_lshl_b32 s24, s24, 14
	global_load_lds_dwordx4 v[142:143], off
	v_lshl_add_u64 v[142:143], v[68:69], 1, s[0:1]
	v_mfma_f32_16x16x32_bf16 v[12:15], v[178:181], v[174:177], v[12:15]
	s_mov_b32 m0, s25
	s_and_b32 s24, s24, 0xe0000
	global_load_lds_dwordx4 v[142:143], off
	v_lshl_add_u64 v[142:143], v[70:71], 1, s[0:1]
	v_readfirstlane_b32 s0, v161
	v_mfma_f32_16x16x32_bf16 v[8:11], v[182:185], v[174:177], v[8:11]
	s_mov_b32 m0, s0
	s_add_u32 s0, s12, s24
	s_addc_u32 s1, s13, 0
	v_readfirstlane_b32 s12, v153
	global_load_lds_dwordx4 v[142:143], off
	v_mfma_f32_16x16x32_bf16 v[4:7], v[186:189], v[174:177], v[4:7]
	v_lshl_add_u64 v[142:143], v[72:73], 1, s[0:1]
	s_mov_b32 m0, s12
	s_nop 0
	global_load_lds_dwordx4 v[142:143], off
	v_lshl_add_u64 v[142:143], v[74:75], 1, s[0:1]
	v_mfma_f32_16x16x32_bf16 v[0:3], v[190:193], v[174:177], v[0:3]
	v_readfirstlane_b32 s0, v152
	s_mov_b32 m0, s0
	s_nop 0
	global_load_lds_dwordx4 v[142:143], off

	s_waitcnt vmcnt(6)
	s_branch .Lp6_m0_done
.Lp6_m0_plain:
	v_mfma_f32_16x16x32_bf16 v[60:63], v[178:181], v[162:165], v[60:63]
	v_mfma_f32_16x16x32_bf16 v[56:59], v[182:185], v[162:165], v[56:59]
	v_mfma_f32_16x16x32_bf16 v[52:55], v[186:189], v[162:165], v[52:55]
	v_mfma_f32_16x16x32_bf16 v[48:51], v[190:193], v[162:165], v[48:51]
	v_mfma_f32_16x16x32_bf16 v[44:47], v[178:181], v[166:169], v[44:47]
	v_mfma_f32_16x16x32_bf16 v[40:43], v[182:185], v[166:169], v[40:43]
	v_mfma_f32_16x16x32_bf16 v[36:39], v[186:189], v[166:169], v[36:39]
	v_mfma_f32_16x16x32_bf16 v[32:35], v[190:193], v[166:169], v[32:35]
	v_mfma_f32_16x16x32_bf16 v[28:31], v[178:181], v[170:173], v[28:31]
	v_mfma_f32_16x16x32_bf16 v[24:27], v[182:185], v[170:173], v[24:27]
	v_mfma_f32_16x16x32_bf16 v[20:23], v[186:189], v[170:173], v[20:23]
	v_mfma_f32_16x16x32_bf16 v[16:19], v[190:193], v[170:173], v[16:19]
	v_mfma_f32_16x16x32_bf16 v[12:15], v[178:181], v[174:177], v[12:15]
	v_mfma_f32_16x16x32_bf16 v[8:11], v[182:185], v[174:177], v[8:11]
	v_mfma_f32_16x16x32_bf16 v[4:7], v[186:189], v[174:177], v[4:7]
	v_mfma_f32_16x16x32_bf16 v[0:3], v[190:193], v[174:177], v[0:3]

	s_waitcnt vmcnt(0)
.Lp6_m0_done:
	s_waitcnt lgkmcnt(0)
	s_barrier
	s_add_i32 s0, s23, 1
	s_mul_hi_u32 s0, s0, 0xaaaaaaab
	s_lshr_b32 s0, s0, 1
	s_mul_i32 s0, s0, 0x24000
	s_add_i32 s1, s20, 0xc000
	v_subrev_u32_e32 v141, s0, v158
	v_add_u32_e32 v140, s1, v156
	v_subrev_u32_e32 v142, s0, v159
	v_add_u32_e32 v141, v140, v141
	ds_read_b128 v[162:165], v141
	ds_read_b128 v[166:169], v141 offset:2048
	ds_read_b128 v[170:173], v141 offset:4096
	ds_read_b128 v[174:177], v141 offset:6144
	v_add_u32_e32 v141, v140, v142
	ds_read_b128 v[178:181], v141 offset:32768
	ds_read_b128 v[182:185], v141 offset:34816
	ds_read_b128 v[186:189], v141 offset:36864
	ds_read_b128 v[190:193], v141 offset:38912

	v_mfma_f32_16x16x32_bf16 v[60:63], v[210:213], v[194:197], v[60:63]
	v_mfma_f32_16x16x32_bf16 v[56:59], v[214:217], v[194:197], v[56:59]
	v_mfma_f32_16x16x32_bf16 v[52:55], v[218:221], v[194:197], v[52:55]
	v_mfma_f32_16x16x32_bf16 v[48:51], v[222:225], v[194:197], v[48:51]
	v_mfma_f32_16x16x32_bf16 v[44:47], v[210:213], v[198:201], v[44:47]
	v_mfma_f32_16x16x32_bf16 v[40:43], v[214:217], v[198:201], v[40:43]
	v_mfma_f32_16x16x32_bf16 v[36:39], v[218:221], v[198:201], v[36:39]
	v_mfma_f32_16x16x32_bf16 v[32:35], v[222:225], v[198:201], v[32:35]
	v_mfma_f32_16x16x32_bf16 v[28:31], v[210:213], v[202:205], v[28:31]
	v_mfma_f32_16x16x32_bf16 v[24:27], v[214:217], v[202:205], v[24:27]
	v_mfma_f32_16x16x32_bf16 v[20:23], v[218:221], v[202:205], v[20:23]
	v_mfma_f32_16x16x32_bf16 v[16:19], v[222:225], v[202:205], v[16:19]
	v_mfma_f32_16x16x32_bf16 v[12:15], v[210:213], v[206:209], v[12:15]
	v_mfma_f32_16x16x32_bf16 v[8:11], v[214:217], v[206:209], v[8:11]
	v_mfma_f32_16x16x32_bf16 v[4:7], v[218:221], v[206:209], v[4:7]
	v_mfma_f32_16x16x32_bf16 v[0:3], v[222:225], v[206:209], v[0:3]

	s_and_b32 s0, s23, 7
	s_cmp_lg_u32 s0, 7
	s_cbranch_scc1 .Lp6_latch
	s_lshr_b32 s4, s4, 4
	s_mul_i32 s0, s4, 24
	s_sub_i32 s0, s23, s0
	s_lshr_b32 s12, s0, 3
	s_load_dword s0, s[38:39], 0x10
	v_mov_b64_e32 v[142:143], s[6:7]
	s_waitcnt lgkmcnt(0)
	s_lshr_b32 s0, s0, 16
	s_cmp_lg_u32 s0, 0
	s_cselect_b64 s[0:1], -1, 0
	s_cmp_lg_u64 s[0:1], 0
	s_addc_u32 s0, s40, 0
	s_mul_i32 s0, s0, s4
	s_add_i32 s0, s0, s2
	s_lshr_b32 s4, s0, 3
	s_and_b32 s1, s0, 7
	s_and_b32 s4, s4, 0xfffff8
	s_or_b32 s1, s4, s1
	s_lshl_b32 s0, s0, 4
	v_lshl_add_u32 v140, s1, 8, v154
	s_and_b32 s0, s0, 0x380
	v_or_b32_e32 v141, s0, v155
	v_mad_i64_i32 v[152:153], s[0:1], v140, s62, v[142:143]
	s_lshl_b32 s80, s12, 11
	v_lshl_add_u64 v[152:153], v[152:153], 0, s[80:81]
	v_lshlrev_b32_e32 v144, 1, v141
	v_lshl_add_u64 v[194:195], v[152:153], 0, v[144:145]
	v_lshl_add_u64 v[152:153], v[194:195], 0, s[90:91]
	v_add_co_u32_e32 v194, vcc, s47, v194
	s_cmp_lg_u32 s12, 2
	s_nop 0
	v_addc_co_u32_e32 v195, vcc, 0, v195, vcc
	v_mov_b32_e32 v198, v152
	v_mov_b32_e32 v199, v153
	s_mov_b64 s[0:1], 0x42000
	v_lshl_add_u64 v[202:203], v[194:195], 0, s[0:1]
	v_lshl_add_u64 v[206:207], v[198:199], 0, s[0:1]
	v_lshl_add_u64 v[210:211], v[202:203], 0, s[0:1]
	v_lshl_add_u64 v[214:215], v[206:207], 0, s[0:1]
	v_lshl_add_u64 v[218:219], v[210:211], 0, s[0:1]
	v_lshl_add_u64 v[222:223], v[214:215], 0, s[0:1]
	global_load_dwordx4 v[194:197], v[194:195], off offset:2304
	global_load_dwordx4 v[198:201], v[198:199], off offset:64
	global_load_dwordx4 v[202:205], v[202:203], off offset:2304
	global_load_dwordx4 v[206:209], v[206:207], off offset:64
	global_load_dwordx4 v[210:213], v[210:211], off offset:2304
	global_load_dwordx4 v[214:217], v[214:215], off offset:64
	global_load_dwordx4 v[218:221], v[218:219], off offset:2304
	global_load_dwordx4 v[222:225], v[222:223], off offset:64
	s_waitcnt vmcnt(7)
	v_lshlrev_b32_e32 v152, 16, v194
	v_and_b32_e32 v153, 0xffff0000, v194
	v_mul_f32_e32 v152, 0xbfb8aa3b, v152
	v_mul_f32_e32 v153, 0xbfb8aa3b, v153
	v_exp_f32_e32 v152, v152
	v_exp_f32_e32 v153, v153
	v_add_f32_e32 v152, 1.0, v152
	v_add_f32_e32 v153, 1.0, v153
	v_rcp_f32_e32 v152, v152
	v_rcp_f32_e32 v153, v153
	s_nop 0
	v_pk_fma_f32 v[138:139], v[60:61], v[152:153], v[138:139]
	v_lshlrev_b32_e32 v142, 16, v195
	v_and_b32_e32 v143, 0xffff0000, v195
	v_mul_f32_e32 v142, 0xbfb8aa3b, v142
	v_mul_f32_e32 v143, 0xbfb8aa3b, v143
	v_exp_f32_e32 v142, v142
	v_exp_f32_e32 v143, v143
	v_add_f32_e32 v142, 1.0, v142
	v_add_f32_e32 v143, 1.0, v143
	v_rcp_f32_e32 v142, v142
	v_rcp_f32_e32 v143, v143
	s_nop 0
	v_pk_fma_f32 v[136:137], v[62:63], v[142:143], v[136:137]
	v_lshlrev_b32_e32 v152, 16, v196
	v_and_b32_e32 v153, 0xffff0000, v196
	v_mul_f32_e32 v152, 0xbfb8aa3b, v152
	v_mul_f32_e32 v153, 0xbfb8aa3b, v153
	v_exp_f32_e32 v152, v152
	v_exp_f32_e32 v153, v153
	v_add_f32_e32 v152, 1.0, v152
	v_add_f32_e32 v153, 1.0, v153
	v_rcp_f32_e32 v152, v152
	v_rcp_f32_e32 v153, v153
	s_nop 0
	v_pk_fma_f32 v[134:135], v[56:57], v[152:153], v[134:135]
	v_lshlrev_b32_e32 v142, 16, v197
	v_and_b32_e32 v143, 0xffff0000, v197
	v_mul_f32_e32 v142, 0xbfb8aa3b, v142
	v_mul_f32_e32 v143, 0xbfb8aa3b, v143
	v_exp_f32_e32 v142, v142
	v_exp_f32_e32 v143, v143
	v_add_f32_e32 v142, 1.0, v142
	v_add_f32_e32 v143, 1.0, v143
	v_rcp_f32_e32 v142, v142
	v_rcp_f32_e32 v143, v143
	s_nop 0
	v_pk_fma_f32 v[132:133], v[58:59], v[142:143], v[132:133]
	s_waitcnt vmcnt(6)
	v_lshlrev_b32_e32 v152, 16, v198
	v_and_b32_e32 v153, 0xffff0000, v198
	v_mul_f32_e32 v152, 0xbfb8aa3b, v152
	v_mul_f32_e32 v153, 0xbfb8aa3b, v153
	v_exp_f32_e32 v152, v152
	v_exp_f32_e32 v153, v153
	v_add_f32_e32 v152, 1.0, v152
	v_add_f32_e32 v153, 1.0, v153
	v_rcp_f32_e32 v152, v152
	v_rcp_f32_e32 v153, v153
	s_nop 0
	v_pk_fma_f32 v[130:131], v[52:53], v[152:153], v[130:131]
	v_lshlrev_b32_e32 v142, 16, v199
	v_and_b32_e32 v143, 0xffff0000, v199
	v_mul_f32_e32 v142, 0xbfb8aa3b, v142
	v_mul_f32_e32 v143, 0xbfb8aa3b, v143
	v_exp_f32_e32 v142, v142
	v_exp_f32_e32 v143, v143
	v_add_f32_e32 v142, 1.0, v142
	v_add_f32_e32 v143, 1.0, v143
	v_rcp_f32_e32 v142, v142
	v_rcp_f32_e32 v143, v143
	s_nop 0
	v_pk_fma_f32 v[128:129], v[54:55], v[142:143], v[128:129]
	v_lshlrev_b32_e32 v152, 16, v200
	v_and_b32_e32 v153, 0xffff0000, v200
	v_mul_f32_e32 v152, 0xbfb8aa3b, v152
	v_mul_f32_e32 v153, 0xbfb8aa3b, v153
	v_exp_f32_e32 v152, v152
	v_exp_f32_e32 v153, v153
	v_add_f32_e32 v152, 1.0, v152
	v_add_f32_e32 v153, 1.0, v153
	v_rcp_f32_e32 v152, v152
	v_rcp_f32_e32 v153, v153
	s_nop 0
	v_pk_fma_f32 v[126:127], v[48:49], v[152:153], v[126:127]
	v_lshlrev_b32_e32 v142, 16, v201
	v_and_b32_e32 v143, 0xffff0000, v201
	v_mul_f32_e32 v142, 0xbfb8aa3b, v142
	v_mul_f32_e32 v143, 0xbfb8aa3b, v143
	v_exp_f32_e32 v142, v142
	v_exp_f32_e32 v143, v143
	v_add_f32_e32 v142, 1.0, v142
	v_add_f32_e32 v143, 1.0, v143
	v_rcp_f32_e32 v142, v142
	v_rcp_f32_e32 v143, v143
	s_nop 0
	v_pk_fma_f32 v[124:125], v[50:51], v[142:143], v[124:125]
	s_waitcnt vmcnt(5)
	v_lshlrev_b32_e32 v152, 16, v202
	v_and_b32_e32 v153, 0xffff0000, v202
	v_mul_f32_e32 v152, 0xbfb8aa3b, v152
	v_mul_f32_e32 v153, 0xbfb8aa3b, v153
	v_exp_f32_e32 v152, v152
	v_exp_f32_e32 v153, v153
	v_add_f32_e32 v152, 1.0, v152
	v_add_f32_e32 v153, 1.0, v153
	v_rcp_f32_e32 v152, v152
	v_rcp_f32_e32 v153, v153
	s_nop 0
	v_pk_fma_f32 v[122:123], v[44:45], v[152:153], v[122:123]
	v_lshlrev_b32_e32 v142, 16, v203
	v_and_b32_e32 v143, 0xffff0000, v203
	v_mul_f32_e32 v142, 0xbfb8aa3b, v142
	v_mul_f32_e32 v143, 0xbfb8aa3b, v143
	v_exp_f32_e32 v142, v142
	v_exp_f32_e32 v143, v143
	v_add_f32_e32 v142, 1.0, v142
	v_add_f32_e32 v143, 1.0, v143
	v_rcp_f32_e32 v142, v142
	v_rcp_f32_e32 v143, v143
	s_nop 0
	v_pk_fma_f32 v[120:121], v[46:47], v[142:143], v[120:121]
	v_lshlrev_b32_e32 v152, 16, v204
	v_and_b32_e32 v153, 0xffff0000, v204
	v_mul_f32_e32 v152, 0xbfb8aa3b, v152
	v_mul_f32_e32 v153, 0xbfb8aa3b, v153
	v_exp_f32_e32 v152, v152
	v_exp_f32_e32 v153, v153
	v_add_f32_e32 v152, 1.0, v152
	v_add_f32_e32 v153, 1.0, v153
	v_rcp_f32_e32 v152, v152
	v_rcp_f32_e32 v153, v153
	s_nop 0
	v_pk_fma_f32 v[118:119], v[40:41], v[152:153], v[118:119]
	v_lshlrev_b32_e32 v142, 16, v205
	v_and_b32_e32 v143, 0xffff0000, v205
	v_mul_f32_e32 v142, 0xbfb8aa3b, v142
	v_mul_f32_e32 v143, 0xbfb8aa3b, v143
	v_exp_f32_e32 v142, v142
	v_exp_f32_e32 v143, v143
	v_add_f32_e32 v142, 1.0, v142
	v_add_f32_e32 v143, 1.0, v143
	v_rcp_f32_e32 v142, v142
	v_rcp_f32_e32 v143, v143
	s_nop 0
	v_pk_fma_f32 v[116:117], v[42:43], v[142:143], v[116:117]
	s_waitcnt vmcnt(4)
	v_lshlrev_b32_e32 v152, 16, v206
	v_and_b32_e32 v153, 0xffff0000, v206
	v_mul_f32_e32 v152, 0xbfb8aa3b, v152
	v_mul_f32_e32 v153, 0xbfb8aa3b, v153
	v_exp_f32_e32 v152, v152
	v_exp_f32_e32 v153, v153
	v_add_f32_e32 v152, 1.0, v152
	v_add_f32_e32 v153, 1.0, v153
	v_rcp_f32_e32 v152, v152
	v_rcp_f32_e32 v153, v153
	s_nop 0
	v_pk_fma_f32 v[114:115], v[36:37], v[152:153], v[114:115]
	v_lshlrev_b32_e32 v142, 16, v207
	v_and_b32_e32 v143, 0xffff0000, v207
	v_mul_f32_e32 v142, 0xbfb8aa3b, v142
	v_mul_f32_e32 v143, 0xbfb8aa3b, v143
	v_exp_f32_e32 v142, v142
	v_exp_f32_e32 v143, v143
	v_add_f32_e32 v142, 1.0, v142
	v_add_f32_e32 v143, 1.0, v143
	v_rcp_f32_e32 v142, v142
	v_rcp_f32_e32 v143, v143
	s_nop 0
	v_pk_fma_f32 v[112:113], v[38:39], v[142:143], v[112:113]
	v_lshlrev_b32_e32 v152, 16, v208
	v_and_b32_e32 v153, 0xffff0000, v208
	v_mul_f32_e32 v152, 0xbfb8aa3b, v152
	v_mul_f32_e32 v153, 0xbfb8aa3b, v153
	v_exp_f32_e32 v152, v152
	v_exp_f32_e32 v153, v153
	v_add_f32_e32 v152, 1.0, v152
	v_add_f32_e32 v153, 1.0, v153
	v_rcp_f32_e32 v152, v152
	v_rcp_f32_e32 v153, v153
	s_nop 0
	v_pk_fma_f32 v[110:111], v[32:33], v[152:153], v[110:111]
	v_lshlrev_b32_e32 v142, 16, v209
	v_and_b32_e32 v143, 0xffff0000, v209
	v_mul_f32_e32 v142, 0xbfb8aa3b, v142
	v_mul_f32_e32 v143, 0xbfb8aa3b, v143
	v_exp_f32_e32 v142, v142
	v_exp_f32_e32 v143, v143
	v_add_f32_e32 v142, 1.0, v142
	v_add_f32_e32 v143, 1.0, v143
	v_rcp_f32_e32 v142, v142
	v_rcp_f32_e32 v143, v143
	s_nop 0
	v_pk_fma_f32 v[108:109], v[34:35], v[142:143], v[108:109]
	s_waitcnt vmcnt(3)
	v_lshlrev_b32_e32 v152, 16, v210
	v_and_b32_e32 v153, 0xffff0000, v210
	v_mul_f32_e32 v152, 0xbfb8aa3b, v152
	v_mul_f32_e32 v153, 0xbfb8aa3b, v153
	v_exp_f32_e32 v152, v152
	v_exp_f32_e32 v153, v153
	v_add_f32_e32 v152, 1.0, v152
	v_add_f32_e32 v153, 1.0, v153
	v_rcp_f32_e32 v152, v152
	v_rcp_f32_e32 v153, v153
	s_nop 0
	v_pk_fma_f32 v[106:107], v[28:29], v[152:153], v[106:107]
	v_lshlrev_b32_e32 v142, 16, v211
	v_and_b32_e32 v143, 0xffff0000, v211
	v_mul_f32_e32 v142, 0xbfb8aa3b, v142
	v_mul_f32_e32 v143, 0xbfb8aa3b, v143
	v_exp_f32_e32 v142, v142
	v_exp_f32_e32 v143, v143
	v_add_f32_e32 v142, 1.0, v142
	v_add_f32_e32 v143, 1.0, v143
	v_rcp_f32_e32 v142, v142
	v_rcp_f32_e32 v143, v143
	s_nop 0
	v_pk_fma_f32 v[104:105], v[30:31], v[142:143], v[104:105]
	v_lshlrev_b32_e32 v152, 16, v212
	v_and_b32_e32 v153, 0xffff0000, v212
	v_mul_f32_e32 v152, 0xbfb8aa3b, v152
	v_mul_f32_e32 v153, 0xbfb8aa3b, v153
	v_exp_f32_e32 v152, v152
	v_exp_f32_e32 v153, v153
	v_add_f32_e32 v152, 1.0, v152
	v_add_f32_e32 v153, 1.0, v153
	v_rcp_f32_e32 v152, v152
	v_rcp_f32_e32 v153, v153
	s_nop 0
	v_pk_fma_f32 v[102:103], v[24:25], v[152:153], v[102:103]
	v_lshlrev_b32_e32 v142, 16, v213
	v_and_b32_e32 v143, 0xffff0000, v213
	v_mul_f32_e32 v142, 0xbfb8aa3b, v142
	v_mul_f32_e32 v143, 0xbfb8aa3b, v143
	v_exp_f32_e32 v142, v142
	v_exp_f32_e32 v143, v143
	v_add_f32_e32 v142, 1.0, v142
	v_add_f32_e32 v143, 1.0, v143
	v_rcp_f32_e32 v142, v142
	v_rcp_f32_e32 v143, v143
	s_nop 0
	v_pk_fma_f32 v[100:101], v[26:27], v[142:143], v[100:101]
	s_waitcnt vmcnt(2)
	v_lshlrev_b32_e32 v152, 16, v214
	v_and_b32_e32 v153, 0xffff0000, v214
	v_mul_f32_e32 v152, 0xbfb8aa3b, v152
	v_mul_f32_e32 v153, 0xbfb8aa3b, v153
	v_exp_f32_e32 v152, v152
	v_exp_f32_e32 v153, v153
	v_add_f32_e32 v152, 1.0, v152
	v_add_f32_e32 v153, 1.0, v153
	v_rcp_f32_e32 v152, v152
	v_rcp_f32_e32 v153, v153
	s_nop 0
	v_pk_fma_f32 v[98:99], v[20:21], v[152:153], v[98:99]
	v_lshlrev_b32_e32 v142, 16, v215
	v_and_b32_e32 v143, 0xffff0000, v215
	v_mul_f32_e32 v142, 0xbfb8aa3b, v142
	v_mul_f32_e32 v143, 0xbfb8aa3b, v143
	v_exp_f32_e32 v142, v142
	v_exp_f32_e32 v143, v143
	v_add_f32_e32 v142, 1.0, v142
	v_add_f32_e32 v143, 1.0, v143
	v_rcp_f32_e32 v142, v142
	v_rcp_f32_e32 v143, v143
	s_nop 0
	v_pk_fma_f32 v[96:97], v[22:23], v[142:143], v[96:97]
	v_lshlrev_b32_e32 v152, 16, v216
	v_and_b32_e32 v153, 0xffff0000, v216
	v_mul_f32_e32 v152, 0xbfb8aa3b, v152
	v_mul_f32_e32 v153, 0xbfb8aa3b, v153
	v_exp_f32_e32 v152, v152
	v_exp_f32_e32 v153, v153
	v_add_f32_e32 v152, 1.0, v152
	v_add_f32_e32 v153, 1.0, v153
	v_rcp_f32_e32 v152, v152
	v_rcp_f32_e32 v153, v153
	s_nop 0
	v_pk_fma_f32 v[94:95], v[16:17], v[152:153], v[94:95]
	v_lshlrev_b32_e32 v142, 16, v217
	v_and_b32_e32 v143, 0xffff0000, v217
	v_mul_f32_e32 v142, 0xbfb8aa3b, v142
	v_mul_f32_e32 v143, 0xbfb8aa3b, v143
	v_exp_f32_e32 v142, v142
	v_exp_f32_e32 v143, v143
	v_add_f32_e32 v142, 1.0, v142
	v_add_f32_e32 v143, 1.0, v143
	v_rcp_f32_e32 v142, v142
	v_rcp_f32_e32 v143, v143
	s_nop 0
	v_pk_fma_f32 v[92:93], v[18:19], v[142:143], v[92:93]
	s_waitcnt vmcnt(1)
	v_lshlrev_b32_e32 v152, 16, v218
	v_and_b32_e32 v153, 0xffff0000, v218
	v_mul_f32_e32 v152, 0xbfb8aa3b, v152
	v_mul_f32_e32 v153, 0xbfb8aa3b, v153
	v_exp_f32_e32 v152, v152
	v_exp_f32_e32 v153, v153
	v_add_f32_e32 v152, 1.0, v152
	v_add_f32_e32 v153, 1.0, v153
	v_rcp_f32_e32 v152, v152
	v_rcp_f32_e32 v153, v153
	s_nop 0
	v_pk_fma_f32 v[90:91], v[12:13], v[152:153], v[90:91]
	v_lshlrev_b32_e32 v142, 16, v219
	v_and_b32_e32 v143, 0xffff0000, v219
	v_mul_f32_e32 v142, 0xbfb8aa3b, v142
	v_mul_f32_e32 v143, 0xbfb8aa3b, v143
	v_exp_f32_e32 v142, v142
	v_exp_f32_e32 v143, v143
	v_add_f32_e32 v142, 1.0, v142
	v_add_f32_e32 v143, 1.0, v143
	v_rcp_f32_e32 v142, v142
	v_rcp_f32_e32 v143, v143
	s_nop 0
	v_pk_fma_f32 v[88:89], v[14:15], v[142:143], v[88:89]
	v_lshlrev_b32_e32 v152, 16, v220
	v_and_b32_e32 v153, 0xffff0000, v220
	v_mul_f32_e32 v152, 0xbfb8aa3b, v152
	v_mul_f32_e32 v153, 0xbfb8aa3b, v153
	v_exp_f32_e32 v152, v152
	v_exp_f32_e32 v153, v153
	v_add_f32_e32 v152, 1.0, v152
	v_add_f32_e32 v153, 1.0, v153
	v_rcp_f32_e32 v152, v152
	v_rcp_f32_e32 v153, v153
	s_nop 0
	v_pk_fma_f32 v[86:87], v[8:9], v[152:153], v[86:87]
	v_lshlrev_b32_e32 v142, 16, v221
	v_and_b32_e32 v143, 0xffff0000, v221
	v_mul_f32_e32 v142, 0xbfb8aa3b, v142
	v_mul_f32_e32 v143, 0xbfb8aa3b, v143
	v_exp_f32_e32 v142, v142
	v_exp_f32_e32 v143, v143
	v_add_f32_e32 v142, 1.0, v142
	v_add_f32_e32 v143, 1.0, v143
	v_rcp_f32_e32 v142, v142
	v_rcp_f32_e32 v143, v143
	s_nop 0
	v_pk_fma_f32 v[84:85], v[10:11], v[142:143], v[84:85]
	s_waitcnt vmcnt(0)
	v_lshlrev_b32_e32 v152, 16, v222
	v_and_b32_e32 v153, 0xffff0000, v222
	v_mul_f32_e32 v152, 0xbfb8aa3b, v152
	v_mul_f32_e32 v153, 0xbfb8aa3b, v153
	v_exp_f32_e32 v152, v152
	v_exp_f32_e32 v153, v153
	v_add_f32_e32 v152, 1.0, v152
	v_add_f32_e32 v153, 1.0, v153
	v_rcp_f32_e32 v152, v152
	v_rcp_f32_e32 v153, v153
	s_nop 0
	v_pk_fma_f32 v[82:83], v[4:5], v[152:153], v[82:83]
	v_lshlrev_b32_e32 v142, 16, v223
	v_and_b32_e32 v143, 0xffff0000, v223
	v_mul_f32_e32 v142, 0xbfb8aa3b, v142
	v_mul_f32_e32 v143, 0xbfb8aa3b, v143
	v_exp_f32_e32 v142, v142
	v_exp_f32_e32 v143, v143
	v_add_f32_e32 v142, 1.0, v142
	v_add_f32_e32 v143, 1.0, v143
	v_rcp_f32_e32 v142, v142
	v_rcp_f32_e32 v143, v143
	s_nop 0
	v_pk_fma_f32 v[80:81], v[6:7], v[142:143], v[80:81]
	v_lshlrev_b32_e32 v152, 16, v224
	v_and_b32_e32 v153, 0xffff0000, v224
	v_mul_f32_e32 v152, 0xbfb8aa3b, v152
	v_mul_f32_e32 v153, 0xbfb8aa3b, v153
	v_exp_f32_e32 v152, v152
	v_exp_f32_e32 v153, v153
	v_add_f32_e32 v152, 1.0, v152
	v_add_f32_e32 v153, 1.0, v153
	v_rcp_f32_e32 v152, v152
	v_rcp_f32_e32 v153, v153
	s_nop 0
	v_pk_fma_f32 v[76:77], v[0:1], v[152:153], v[76:77]
	v_lshlrev_b32_e32 v142, 16, v225
	v_and_b32_e32 v143, 0xffff0000, v225
	v_mul_f32_e32 v142, 0xbfb8aa3b, v142
	v_mul_f32_e32 v143, 0xbfb8aa3b, v143
	v_exp_f32_e32 v142, v142
	v_exp_f32_e32 v143, v143
	v_add_f32_e32 v142, 1.0, v142
	v_add_f32_e32 v143, 1.0, v143
	v_rcp_f32_e32 v142, v142
	v_rcp_f32_e32 v143, v143
	s_nop 0
	v_pk_fma_f32 v[78:79], v[2:3], v[142:143], v[78:79]
	v_or_b32_e32 v48, 16, v140
	v_or_b32_e32 v32, 32, v140
	v_or_b32_e32 v16, 48, v140
	s_cbranch_scc1 .LBB0_967
	v_ashrrev_i32_e32 v141, 31, v140
	v_lshl_add_u64 v[4:5], s[8:9], 0, v[144:145]
	v_lshlrev_b64 v[0:1], 11, v[140:141]
	v_lshl_add_u64 v[6:7], v[4:5], 0, v[0:1]
	v_cvt_pk_bf16_f32 v0, v138, v139
	v_cvt_pk_bf16_f32 v1, v136, v137
	v_ashrrev_i32_e32 v49, 31, v48
	v_cvt_pk_bf16_f32 v2, v134, v135
	v_cvt_pk_bf16_f32 v3, v132, v133
	global_store_dwordx4 v[6:7], v[0:3], off
	v_ashrrev_i32_e32 v33, 31, v32
	v_ashrrev_i32_e32 v17, 31, v16
	v_cvt_pk_bf16_f32 v0, v130, v131
	v_cvt_pk_bf16_f32 v1, v128, v129
	v_cvt_pk_bf16_f32 v2, v126, v127
	v_cvt_pk_bf16_f32 v3, v124, v125
	global_store_dwordx4 v[6:7], v[0:3], off offset:64
	v_mov_b32_e32 v137, 0
	v_mov_b32_e32 v136, v137
	v_lshlrev_b64 v[0:1], 11, v[48:49]
	v_lshl_add_u64 v[6:7], v[4:5], 0, v[0:1]
	v_cvt_pk_bf16_f32 v0, v122, v123
	v_cvt_pk_bf16_f32 v1, v120, v121
	v_cvt_pk_bf16_f32 v2, v118, v119
	v_cvt_pk_bf16_f32 v3, v116, v117
	global_store_dwordx4 v[6:7], v[0:3], off
	v_mov_b32_e32 v139, v137
	v_mov_b32_e32 v138, v137
	v_cvt_pk_bf16_f32 v0, v114, v115
	v_cvt_pk_bf16_f32 v1, v112, v113
	v_cvt_pk_bf16_f32 v2, v110, v111
	v_cvt_pk_bf16_f32 v3, v108, v109
	global_store_dwordx4 v[6:7], v[0:3], off offset:64
	v_mov_b32_e32 v133, v137
	v_mov_b32_e32 v132, v137
	v_lshlrev_b64 v[0:1], 11, v[32:33]
	v_lshl_add_u64 v[6:7], v[4:5], 0, v[0:1]
	v_cvt_pk_bf16_f32 v0, v106, v107
	v_cvt_pk_bf16_f32 v1, v104, v105
	v_cvt_pk_bf16_f32 v2, v102, v103
	v_cvt_pk_bf16_f32 v3, v100, v101
	global_store_dwordx4 v[6:7], v[0:3], off
	v_mov_b32_e32 v135, v137
	v_mov_b32_e32 v134, v137
	v_cvt_pk_bf16_f32 v0, v98, v99
	v_cvt_pk_bf16_f32 v1, v96, v97
	v_cvt_pk_bf16_f32 v2, v94, v95
	v_cvt_pk_bf16_f32 v3, v92, v93
	global_store_dwordx4 v[6:7], v[0:3], off offset:64
	v_mov_b32_e32 v129, v137
	v_mov_b32_e32 v128, v137
	v_lshlrev_b64 v[0:1], 11, v[16:17]
	v_lshl_add_u64 v[4:5], v[4:5], 0, v[0:1]
	v_cvt_pk_bf16_f32 v0, v90, v91
	v_cvt_pk_bf16_f32 v1, v88, v89
	v_cvt_pk_bf16_f32 v2, v86, v87
	v_cvt_pk_bf16_f32 v3, v84, v85
	global_store_dwordx4 v[4:5], v[0:3], off
	v_mov_b32_e32 v131, v137
	v_mov_b32_e32 v130, v137
	v_cvt_pk_bf16_f32 v0, v82, v83
	v_cvt_pk_bf16_f32 v1, v80, v81
	v_cvt_pk_bf16_f32 v2, v76, v77
	v_cvt_pk_bf16_f32 v3, v78, v79
	v_mov_b32_e32 v125, v137
	v_mov_b32_e32 v124, v137
	v_mov_b32_e32 v127, v137
	v_mov_b32_e32 v126, v137
	v_mov_b32_e32 v121, v137
	v_mov_b32_e32 v120, v137
	v_mov_b32_e32 v123, v137
	v_mov_b32_e32 v122, v137
	v_mov_b32_e32 v117, v137
	v_mov_b32_e32 v116, v137
	v_mov_b32_e32 v119, v137
	v_mov_b32_e32 v118, v137
	v_mov_b32_e32 v113, v137
	v_mov_b32_e32 v112, v137
	v_mov_b32_e32 v115, v137
	v_mov_b32_e32 v114, v137
	v_mov_b32_e32 v109, v137
	v_mov_b32_e32 v108, v137
	v_mov_b32_e32 v111, v137
	v_mov_b32_e32 v110, v137
	v_mov_b32_e32 v105, v137
	v_mov_b32_e32 v104, v137
	v_mov_b32_e32 v107, v137
	v_mov_b32_e32 v106, v137
	v_mov_b32_e32 v101, v137
	v_mov_b32_e32 v100, v137
	v_mov_b32_e32 v103, v137
	v_mov_b32_e32 v102, v137
	v_mov_b32_e32 v97, v137
	v_mov_b32_e32 v96, v137
	v_mov_b32_e32 v99, v137
	v_mov_b32_e32 v98, v137
	v_mov_b32_e32 v93, v137
	v_mov_b32_e32 v92, v137
	v_mov_b32_e32 v95, v137
	v_mov_b32_e32 v94, v137
	v_mov_b32_e32 v89, v137
	v_mov_b32_e32 v88, v137
	v_mov_b32_e32 v91, v137
	v_mov_b32_e32 v90, v137
	v_mov_b32_e32 v85, v137
	v_mov_b32_e32 v84, v137
	v_mov_b32_e32 v87, v137
	v_mov_b32_e32 v86, v137
	v_mov_b32_e32 v81, v137
	v_mov_b32_e32 v80, v137
	v_mov_b32_e32 v83, v137
	v_mov_b32_e32 v82, v137
	v_mov_b32_e32 v79, v137
	v_mov_b32_e32 v78, v137
	v_mov_b32_e32 v77, v137
	v_mov_b32_e32 v76, v137
	global_store_dwordx4 v[4:5], v[0:3], off offset:64
